# attention: wave-invariant LDS-DMA destination selects removed
# baseline (speedup 1.0000x reference)
.Lv1p_body:
	s_cmp_gt_u32 s8, 61
	s_cselect_b64 s[78:79], -1, 0
	s_and_b64 vcc, exec, s[78:79]
	s_cbranch_vccnz .LBB0_625
	s_mul_i32 s16, s56, 0x9000
	s_add_i32 m0, s16, s35
	s_nop 0
	global_load_lds_dwordx4 v[240:241], off
	s_add_i32 m0, s16, s33
	v_lshl_add_u64 v[240:241], v[240:241], 0, v[200:201]
	global_load_lds_dwordx4 v[242:243], off
	s_add_i32 m0, s16, s93
	v_lshl_add_u64 v[242:243], v[242:243], 0, v[202:203]
	global_load_lds_dwordx4 v[244:245], off
	s_add_i32 m0, s16, s45
	v_lshl_add_u64 v[244:245], v[244:245], 0, v[204:205]
	global_load_lds_dwordx4 v[246:247], off
	s_mov_b32 m0, s27
	v_lshl_add_u64 v[246:247], v[246:247], 0, v[206:207]
	global_load_lds_dwordx4 v[248:249], off
	v_lshl_add_u64 v[248:249], v[248:249], 0, v[208:209]

.LBB0_643:
	v_add_u32_e32 v128, s50, v164
	s_waitcnt lgkmcnt(0)
	s_barrier
	v_add_u32_e32 v168, v128, v165
	ds_read_b128 v[140:143], v168 offset:18432
	ds_read_b128 v[132:135], v168 offset:18448
	ds_read_b128 v[136:139], v168 offset:23040
	ds_read_b128 v[128:131], v168 offset:23056
	ds_read_b128 v[178:181], v168 offset:27648
	ds_read_b128 v[182:185], v168 offset:27664
	ds_read_b128 v[186:189], v168 offset:32256
	ds_read_b128 v[190:193], v168 offset:32272
	v_exp_f32_e32 v96, v96
	v_exp_f32_e32 v97, v97
	v_exp_f32_e32 v98, v98
	v_exp_f32_e32 v99, v99
	v_exp_f32_e32 v100, v100
	v_exp_f32_e32 v101, v101
	v_exp_f32_e32 v102, v102
	v_exp_f32_e32 v103, v103
	v_exp_f32_e32 v104, v104
	v_exp_f32_e32 v105, v105
	v_exp_f32_e32 v106, v106
	v_exp_f32_e32 v107, v107
	v_exp_f32_e32 v108, v108
	v_exp_f32_e32 v109, v109
	v_exp_f32_e32 v110, v110
	v_exp_f32_e32 v111, v111
	v_cvt_pk_bf16_f32 v170, v96, v97
	v_cvt_pk_bf16_f32 v171, v98, v99
	v_cvt_pk_bf16_f32 v172, v100, v101
	v_cvt_pk_bf16_f32 v173, v102, v103
	v_cvt_pk_bf16_f32 v194, v104, v105
	v_cvt_pk_bf16_f32 v195, v106, v107
	v_cvt_pk_bf16_f32 v196, v108, v109
	v_cvt_pk_bf16_f32 v197, v110, v111
	s_waitcnt lgkmcnt(7)
	v_mfma_f32_32x32x16_bf16 v[48:63], v[140:143], v[170:173], v[48:63]
	v_exp_f32_e32 v80, v80
	v_exp_f32_e32 v81, v81
	v_exp_f32_e32 v82, v82
	v_exp_f32_e32 v83, v83
	s_waitcnt lgkmcnt(5)
	v_mfma_f32_32x32x16_bf16 v[0:15], v[136:139], v[170:173], v[0:15]
	v_mfma_f32_32x32x16_bf16 v[48:63], v[132:135], v[194:197], v[48:63]
	v_exp_f32_e32 v84, v84
	v_exp_f32_e32 v85, v85
	v_exp_f32_e32 v86, v86
	v_exp_f32_e32 v87, v87
	s_waitcnt lgkmcnt(4)
	v_mfma_f32_32x32x16_bf16 v[0:15], v[128:131], v[194:197], v[0:15]
	ds_read_b128 v[128:131], v168 offset:18496
	ds_read_b128 v[132:135], v168 offset:18512
	ds_read_b128 v[136:139], v168 offset:23104
	ds_read_b128 v[140:143], v168 offset:23120
	s_waitcnt lgkmcnt(7)
	v_mfma_f32_32x32x16_bf16 v[32:47], v[178:181], v[170:173], v[32:47]
	v_exp_f32_e32 v88, v88
	v_exp_f32_e32 v89, v89
	v_exp_f32_e32 v90, v90
	v_exp_f32_e32 v91, v91
	s_waitcnt lgkmcnt(5)
	v_mfma_f32_32x32x16_bf16 v[16:31], v[186:189], v[170:173], v[16:31]
	v_mfma_f32_32x32x16_bf16 v[32:47], v[182:185], v[194:197], v[32:47]
	v_exp_f32_e32 v92, v92
	v_exp_f32_e32 v93, v93
	v_exp_f32_e32 v94, v94
	v_exp_f32_e32 v95, v95
	v_cvt_pk_bf16_f32 v170, v80, v81
	v_cvt_pk_bf16_f32 v171, v82, v83
	v_cvt_pk_bf16_f32 v172, v84, v85
	s_waitcnt lgkmcnt(4)
	v_mfma_f32_32x32x16_bf16 v[16:31], v[190:193], v[194:197], v[16:31]
	v_cvt_pk_bf16_f32 v173, v86, v87
	v_cvt_pk_bf16_f32 v178, v88, v89
	v_cvt_pk_bf16_f32 v179, v90, v91
	v_cvt_pk_bf16_f32 v180, v92, v93
	v_cvt_pk_bf16_f32 v181, v94, v95
	ds_read_b128 v[182:185], v168 offset:27712
	ds_read_b128 v[186:189], v168 offset:27728
	ds_read_b128 v[190:193], v168 offset:32320
	ds_read_b128 v[194:197], v168 offset:32336
	s_cmp_gt_u32 s33, 61
	s_cselect_b64 s[50:51], -1, 0
	s_and_b64 vcc, exec, s[50:51]
	s_cbranch_vccnz .LBB0_645
	s_mul_i32 s63, s45, 0x9000
	s_or_b32 m0, s63, s35
	s_nop 0
	global_load_lds_dwordx4 v[240:241], off
	s_add_i32 m0, s2, s63
	v_lshl_add_u64 v[240:241], v[240:241], 0, v[200:201]
	global_load_lds_dwordx4 v[242:243], off
	s_add_i32 m0, s63, s21
	v_lshl_add_u64 v[242:243], v[242:243], 0, v[202:203]
	global_load_lds_dwordx4 v[244:245], off
	s_add_i32 m0, s26, s63
	v_lshl_add_u64 v[244:245], v[244:245], 0, v[204:205]
	global_load_lds_dwordx4 v[246:247], off
	s_add_i32 m0, s63, s3
	v_lshl_add_u64 v[246:247], v[246:247], 0, v[206:207]
	global_load_lds_dwordx4 v[248:249], off
	v_lshl_add_u64 v[248:249], v[248:249], 0, v[208:209]

.Lv1s_body:
	s_cmp_gt_u32 s8, 29
	s_cselect_b64 s[78:79], -1, 0
	s_and_b64 vcc, exec, s[78:79]
	s_cbranch_vccnz .LBB0_686
	s_mul_i32 vcc_lo, s56, 0x9000
	s_add_i32 m0, vcc_lo, s35
	s_nop 0
	global_load_lds_dwordx4 v[240:241], off
	s_add_i32 m0, vcc_lo, s33
	v_lshl_add_u64 v[240:241], v[240:241], 0, v[200:201]
	global_load_lds_dwordx4 v[242:243], off
	s_add_i32 m0, vcc_lo, s93
	v_lshl_add_u64 v[242:243], v[242:243], 0, v[202:203]
	global_load_lds_dwordx4 v[244:245], off
	s_add_i32 m0, vcc_lo, s45
	v_lshl_add_u64 v[244:245], v[244:245], 0, v[204:205]
	global_load_lds_dwordx4 v[246:247], off
	s_mov_b32 m0, s86
	v_lshl_add_u64 v[246:247], v[246:247], 0, v[206:207]
	global_load_lds_dwordx4 v[248:249], off
	v_lshl_add_u64 v[248:249], v[248:249], 0, v[208:209]

.LBB0_704:
	v_add_u32_e32 v128, s56, v164
	s_waitcnt lgkmcnt(0)
	s_barrier
	v_add_u32_e32 v168, v128, v165
	ds_read_b128 v[140:143], v168 offset:18432
	ds_read_b128 v[132:135], v168 offset:18448
	ds_read_b128 v[136:139], v168 offset:23040
	ds_read_b128 v[128:131], v168 offset:23056
	ds_read_b128 v[178:181], v168 offset:27648
	ds_read_b128 v[182:185], v168 offset:27664
	ds_read_b128 v[186:189], v168 offset:32256
	ds_read_b128 v[190:193], v168 offset:32272
	v_exp_f32_e32 v96, v96
	v_exp_f32_e32 v97, v97
	v_exp_f32_e32 v98, v98
	v_exp_f32_e32 v99, v99
	v_exp_f32_e32 v100, v100
	v_exp_f32_e32 v101, v101
	v_exp_f32_e32 v102, v102
	v_exp_f32_e32 v103, v103
	v_exp_f32_e32 v104, v104
	v_exp_f32_e32 v105, v105
	v_exp_f32_e32 v106, v106
	v_exp_f32_e32 v107, v107
	v_exp_f32_e32 v108, v108
	v_exp_f32_e32 v109, v109
	v_exp_f32_e32 v110, v110
	v_exp_f32_e32 v111, v111
	v_cvt_pk_bf16_f32 v170, v96, v97
	v_cvt_pk_bf16_f32 v171, v98, v99
	v_cvt_pk_bf16_f32 v172, v100, v101
	v_cvt_pk_bf16_f32 v173, v102, v103
	v_cvt_pk_bf16_f32 v194, v104, v105
	v_cvt_pk_bf16_f32 v195, v106, v107
	v_cvt_pk_bf16_f32 v196, v108, v109
	v_cvt_pk_bf16_f32 v197, v110, v111
	s_waitcnt lgkmcnt(7)
	v_mfma_f32_32x32x16_bf16 v[48:63], v[140:143], v[170:173], v[48:63]
	v_exp_f32_e32 v80, v80
	v_exp_f32_e32 v81, v81
	v_exp_f32_e32 v82, v82
	v_exp_f32_e32 v83, v83
	s_waitcnt lgkmcnt(5)
	v_mfma_f32_32x32x16_bf16 v[0:15], v[136:139], v[170:173], v[0:15]
	v_mfma_f32_32x32x16_bf16 v[48:63], v[132:135], v[194:197], v[48:63]
	v_exp_f32_e32 v84, v84
	v_exp_f32_e32 v85, v85
	v_exp_f32_e32 v86, v86
	v_exp_f32_e32 v87, v87
	s_waitcnt lgkmcnt(4)
	v_mfma_f32_32x32x16_bf16 v[0:15], v[128:131], v[194:197], v[0:15]
	ds_read_b128 v[128:131], v168 offset:18496
	ds_read_b128 v[132:135], v168 offset:18512
	ds_read_b128 v[136:139], v168 offset:23104
	ds_read_b128 v[140:143], v168 offset:23120
	s_waitcnt lgkmcnt(7)
	v_mfma_f32_32x32x16_bf16 v[32:47], v[178:181], v[170:173], v[32:47]
	v_exp_f32_e32 v88, v88
	v_exp_f32_e32 v89, v89
	v_exp_f32_e32 v90, v90
	v_exp_f32_e32 v91, v91
	s_waitcnt lgkmcnt(5)
	v_mfma_f32_32x32x16_bf16 v[16:31], v[186:189], v[170:173], v[16:31]
	v_mfma_f32_32x32x16_bf16 v[32:47], v[182:185], v[194:197], v[32:47]
	v_exp_f32_e32 v92, v92
	v_exp_f32_e32 v93, v93
	v_exp_f32_e32 v94, v94
	v_exp_f32_e32 v95, v95
	v_cvt_pk_bf16_f32 v170, v80, v81
	v_cvt_pk_bf16_f32 v171, v82, v83
	v_cvt_pk_bf16_f32 v172, v84, v85
	s_waitcnt lgkmcnt(4)
	v_mfma_f32_32x32x16_bf16 v[16:31], v[190:193], v[194:197], v[16:31]
	v_cvt_pk_bf16_f32 v173, v86, v87
	v_cvt_pk_bf16_f32 v178, v88, v89
	v_cvt_pk_bf16_f32 v179, v90, v91
	v_cvt_pk_bf16_f32 v180, v92, v93
	v_cvt_pk_bf16_f32 v181, v94, v95
	ds_read_b128 v[182:185], v168 offset:27712
	ds_read_b128 v[186:189], v168 offset:27728
	ds_read_b128 v[190:193], v168 offset:32320
	ds_read_b128 v[194:197], v168 offset:32336
	s_cmp_gt_u32 s33, 29
	s_cselect_b64 s[60:61], -1, 0
	s_and_b64 vcc, exec, s[60:61]
	s_cbranch_vccnz .LBB0_706
	s_mul_i32 s62, s45, 0x9000
	s_or_b32 m0, s62, s35
	s_nop 0
	global_load_lds_dwordx4 v[240:241], off
	s_add_i32 m0, s2, s62
	v_lshl_add_u64 v[240:241], v[240:241], 0, v[200:201]
	global_load_lds_dwordx4 v[242:243], off
	s_add_i32 m0, s62, s21
	v_lshl_add_u64 v[242:243], v[242:243], 0, v[202:203]
	global_load_lds_dwordx4 v[244:245], off
	s_add_i32 m0, s26, s62
	v_lshl_add_u64 v[244:245], v[244:245], 0, v[204:205]
	global_load_lds_dwordx4 v[246:247], off
	s_add_i32 m0, s62, s3
	v_lshl_add_u64 v[246:247], v[246:247], 0, v[206:207]
	global_load_lds_dwordx4 v[248:249], off
	v_lshl_add_u64 v[248:249], v[248:249], 0, v[208:209]
